# C1 RWKV-prep tile head: the 4 activation elements' cur/prev/mu loads issued together before the tile barrier instead of 4 serialized load-wait chains
# speedup vs baseline: 1.0157x; 1.0032x over previous
; __device__ __forceinline__ float bf2f(bf16_t b) { return __uint_as_float((unsigned)b << 16); }
; __global__ void __launch_bounds__(NWAVES * 64, 2) mk_fwd(Args args) {
;     ...
;                     __syncthreads();
; #pragma unroll
;                     for (int e = 0; e < 4; ++e) { const int idx = tid + 512 * e, tok = idx >> 7, i = idx & 127, col = 3072 + i, m = m0 + tok;
;                         const float cur = bf2f(proj[(size_t)m * NPAD + col]);
;                         float prev;
;                         if (tok == 0 && first) prev = smp ? shst[col] : 0.f; else prev = bf2f(proj[(size_t)(m - 1) * NPAD + col]);
.LBB0_429:
	v_add_u32_e32 v4, s80, v55
	s_movk_i32 s56, 0x5e00
	v_mad_i64_i32 v[6:7], s[56:57], v4, s56, v[56:57]
	global_load_dword v206, v[58:59], off
	global_load_ushort v207, v[6:7], off
	s_mov_b64 s[56:57], 0x17800
	v_lshl_add_u64 v[208:209], v[6:7], 0, s[56:57]
	s_mov_b64 s[56:57], 0x11a00
	v_lshl_add_u64 v[212:213], v[6:7], 0, s[56:57]
	global_load_ushort v210, v[208:209], off
	global_load_ushort v211, v[212:213], off
	s_mov_b64 s[56:57], 0x2f000
	v_lshl_add_u64 v[218:219], v[6:7], 0, s[56:57]
	s_mov_b64 s[56:57], 0x29200
	v_lshl_add_u64 v[224:225], v[6:7], 0, s[56:57]
	global_load_ushort v216, v[218:219], off
	global_load_ushort v217, v[224:225], off
	s_mov_b64 s[56:57], 0x46800
	v_lshl_add_u64 v[222:223], v[6:7], 0, s[56:57]
	s_mov_b64 s[56:57], 0x40a00
	v_lshl_add_u64 v[226:227], v[6:7], 0, s[56:57]
	global_load_ushort v220, v[222:223], off
	global_load_ushort v221, v[226:227], off
	s_and_b64 s[56:57], s[42:43], exec
	s_cselect_b32 s58, s59, s58
	s_cselect_b32 s59, s60, s61
	s_cmp_eq_u32 s59, 0
	s_cselect_b64 s[56:57], -1, 0
	s_cmp_lg_u32 s59, 0
	s_cselect_b64 s[88:89], -1, 0
	s_add_i32 s58, s58, s19
	s_mul_hi_i32 s59, s58, 0x3200
	s_mulk_i32 s58, 0x3200
	v_readlane_b32 s74, v252, 50
	v_readlane_b32 s75, v252, 51
	s_nop 3
	s_add_u32 s84, s74, s58
	s_addc_u32 s85, s75, s59
	s_and_b64 s[58:59], s[8:9], s[56:57]
	s_xor_b64 s[58:59], s[58:59], -1
	s_and_saveexec_b64 s[60:61], s[58:59]
	s_xor_b64 s[58:59], exec, s[60:61]
	s_cbranch_execz .LBB0_431
	v_add_u32_e32 v4, -1, v4
	s_movk_i32 s60, 0x5e00
	v_mad_i64_i32 v[4:5], s[60:61], v4, s60, v[56:57]
	global_load_ushort v214, v[4:5], off

; __device__ __forceinline__ float bf2f(bf16_t b) { return __uint_as_float((unsigned)b << 16); }
; __device__ __forceinline__ unsigned cvtpk(float lo, float hi) { unsigned r; asm volatile("v_cvt_pk_bf16_f32 %0, %1, %2" : "=v"(r) : "v"(lo), "v"(hi)); return r; }
; __global__ void __launch_bounds__(NWAVES * 64, 2) mk_fwd(Args args) {
;     ...
;                     for (int e = 0; e < 4; ++e) { const int idx = tid + 512 * e, tok = idx >> 7, i = idx & 127, col = 3072 + i, m = m0 + tok;
;                         const float cur = bf2f(proj[(size_t)m * NPAD + col]);
;                         float prev;
;                         if (tok == 0 && first) prev = smp ? shst[col] : 0.f; else prev = bf2f(proj[(size_t)(m - 1) * NPAD + col]);
;                         float xsv = cur + (prev - cur) * mu[col];
;                         if (i < 64) { const float e2 = __expf(2.f * xsv); xsv = 1.f - 2.f * __builtin_amdgcn_rcpf(e2 + 1.f); }
;                         const float xo = __shfl_xor(xsv, 1);
;                         if (!(i & 1)) actP[(i >> 1) * 16 + tok] = cvtpk(xsv, xo); }
.LBB0_434:
	s_or_b64 exec, exec, s[58:59]
	s_waitcnt vmcnt(0)
	s_barrier
	v_lshlrev_b32_e32 v214, 16, v214
	v_cndmask_b32_e64 v214, v7, v214, s[58:59]
	v_lshlrev_b32_e32 v211, 16, v211
	v_lshlrev_b32_e32 v217, 16, v217
	v_lshlrev_b32_e32 v221, 16, v221
	v_lshlrev_b32_e32 v207, 16, v207
	v_lshlrev_b32_e32 v210, 16, v210
	v_lshlrev_b32_e32 v216, 16, v216
	v_lshlrev_b32_e32 v220, 16, v220
	v_sub_f32_e32 v214, v214, v207
	v_sub_f32_e32 v211, v211, v210
	v_sub_f32_e32 v217, v217, v216
	v_sub_f32_e32 v221, v221, v220
	v_fmac_f32_e32 v207, v214, v206
	v_fmac_f32_e32 v210, v211, v206
	v_fmac_f32_e32 v216, v217, v206
	v_fmac_f32_e32 v220, v221, v206
	v_add_f32_e32 v214, v207, v207
	v_add_f32_e32 v211, v210, v210
	v_add_f32_e32 v217, v216, v216
	v_add_f32_e32 v221, v220, v220
	v_mul_f32_e32 v214, 0x3fb8aa3b, v214
	v_mul_f32_e32 v211, 0x3fb8aa3b, v211
	v_mul_f32_e32 v217, 0x3fb8aa3b, v217
	v_mul_f32_e32 v221, 0x3fb8aa3b, v221
	v_exp_f32_e32 v214, v214
	v_exp_f32_e32 v211, v211
	v_exp_f32_e32 v217, v217
	v_exp_f32_e32 v221, v221
	s_nop 0
	v_add_f32_e32 v214, 1.0, v214
	v_add_f32_e32 v211, 1.0, v211
	v_add_f32_e32 v217, 1.0, v217
	v_add_f32_e32 v221, 1.0, v221
	v_rcp_f32_e32 v214, v214
	v_rcp_f32_e32 v211, v211
	v_rcp_f32_e32 v217, v217
	v_rcp_f32_e32 v221, v221
	s_nop 0
	v_fma_f32 v214, v214, -2.0, 1.0
	v_fma_f32 v211, v211, -2.0, 1.0
	v_fma_f32 v217, v217, -2.0, 1.0
	v_fma_f32 v221, v221, -2.0, 1.0
	v_cndmask_b32_e64 v207, v207, v214, s[2:3]
	v_cndmask_b32_e64 v210, v210, v211, s[2:3]
	v_cndmask_b32_e64 v216, v216, v217, s[2:3]
	v_cndmask_b32_e64 v220, v220, v221, s[2:3]
	ds_bpermute_b32 v214, v88, v207
	ds_bpermute_b32 v211, v88, v210
	ds_bpermute_b32 v217, v88, v216
	ds_bpermute_b32 v221, v88, v220
	s_and_saveexec_b64 s[56:57], s[4:5]
	s_waitcnt lgkmcnt(0)
	v_cvt_pk_bf16_f32 v207, v207, v214
	ds_write_b32 v89, v207
	v_cvt_pk_bf16_f32 v210, v210, v211
	ds_write_b32 v91, v210
	v_cvt_pk_bf16_f32 v216, v216, v217
	ds_write_b32 v93, v216
	v_cvt_pk_bf16_f32 v220, v220, v221
	ds_write_b32 v95, v220
